# attention DMA sequence with s_nop fillers after m0 writes (K DMA split into its own block)
# speedup vs baseline: 1.0539x; 1.0012x over previous
; __device__ __forceinline__ void finishSM(f32x16& p0, f32x16& p1, float alpha, float& l_reg, bf16x8& pa0, bf16x8& pa1, bf16x8& pa2, bf16x8& pa3) {
; #pragma unroll
;   for (int r = 0; r < 16; ++r) p1[r] = __builtin_amdgcn_exp2f(p1[r]);
;   float ps = 0;
; #pragma unroll
;   for (int r = 0; r < 16; ++r) ps += p0[r];
; #pragma unroll
;   for (int r = 0; r < 16; ++r) ps += p1[r];
;   { auto rr = __builtin_amdgcn_permlane32_swap(__float_as_uint(ps), __float_as_uint(ps), false, false);
;     ps = __uint_as_float(rr[0]) + __uint_as_float(rr[1]); }
;   l_reg = l_reg * alpha + ps;
;     ...
;   PK4(p0, 0, pa0); PK4(p0, 8, pa1); PK4(p1, 0, pa2); PK4(p1, 8, pa3);
;     ...
; }
; __device__ __forceinline__ void qkt(f32x16& p0, f32x16& p1, const char* Ks, const bf16x8* qr, int r32, int hi, float m_ref) {
; #pragma unroll
;   for (int r = 0; r < 16; ++r) { p0[r] = -m_ref; p1[r] = -m_ref; }
; #pragma unroll
;   for (int d0 = 0; d0 < 4; ++d0) { const int cb = (d0 * 16 + hi * 8) * 2;
;     bf16x8 b0 = *reinterpret_cast<const bf16x8*>(Ks + KSWZ(r32, cb));
;     bf16x8 b1 = *reinterpret_cast<const bf16x8*>(Ks + KSWZ(32 + r32, cb));
;     p0 = __builtin_amdgcn_mfma_f32_32x32x16_bf16(b0, qr[d0], p0, 0, 0, 0);
;     p1 = __builtin_amdgcn_mfma_f32_32x32x16_bf16(b1, qr[d0], p1, 0, 0, 0); }
; }
; __device__ __forceinline__ int v_st(int k, int c) { const int kk = (k & ~0xC) | ((k & 4) << 1) | ((k & 8) >> 1); return ((kk >> 3) * 4 + (c >> 5)) * 512 + ((kk & 7) * 32 + (c & 31)) * 2; }
; __device__ __forceinline__ int v_rd_base(int lane) { return ((lane & 3) << 3) | (((lane >> 2) & 3) << 6) | (((lane >> 4) & 1) << 5) | (((lane >> 5) & 1) << 8); }
; template <int OFF> __device__ __forceinline__ s16x4 tr_read(int vb) {
; __device__ __forceinline__ void attn_unit(const bf16_t* __restrict__ Qb, const bf16_t* __restrict__ Kh, const bf16_t* __restrict__ Vh, int seq, char* lds,
;                                           int mode, float* scratch, float lam, float gscale, const float* __restrict__ subg, bf16_t* outp) {
;     ...
;   for (int j = 1; j + 1 < NT; j += 2) {
;     SBAR(); qkt(pB0, pB1, K_lds + bc * SHM_K, qr, r32, hi, m_reg);
;     finishSM(pA0, pA1, alA, l_reg, pa0, pa1, pa2, pa3); SBAR();
;     SLOAD(SO, (j + 2) * KVBLK); SBAR();
;     pv_d0(o, vb0 + bp * SHM_V, pa0, pa1, pa2, pa3); partialSM(pB0, pB1, m_reg, alB, false);
;     SWAIT(); SWRITE(bn, SE);
;     RESC(alB); __syncthreads(); ROT3();
.Lat_loop:
	s_mov_b32 s21, 0
	s_lshl_b32 s20, s0, 14
	s_add_i32 s20, s20, s79
	s_add_i32 m0, s20, s79
	s_nop 0
	global_load_lds_dwordx4 v233, s[24:25]
	s_add_i32 m0, m0, 0x400
	s_nop 0
	global_load_lds_dwordx4 v234, s[24:25]
	s_add_i32 s20, s52, 3
	s_and_b32 s20, s20, 3
	s_lshl_b32 s20, s20, 13
	s_add_i32 s20, s20, s79
	s_add_i32 m0, s20, 0xc000
	s_nop 0
	global_load_lds_dwordx4 v232, s[24:25]
	s_add_u32 s24, s24, 0x10000
	s_addc_u32 s25, s25, 0
	v_add_f32_e32 v159, v64, v65
	v_cvt_pk_bf16_f32 v64, v64, v65
	v_add_f32_e32 v160, v66, v67
	v_cvt_pk_bf16_f32 v65, v66, v67
	v_add_f32_e32 v159, v68, v159
	s_waitcnt lgkmcnt(7)
	v_mfma_f32_32x32x16_bf16 v[96:111], v[182:185], v[124:127], v[128:143]
	v_add_f32_e32 v160, v69, v160
	v_cvt_pk_bf16_f32 v66, v68, v69
	v_add_f32_e32 v159, v70, v159
	v_add_f32_e32 v160, v71, v160
	v_cvt_pk_bf16_f32 v67, v70, v71
	v_add_f32_e32 v159, v72, v159
	s_waitcnt lgkmcnt(6)
	v_mfma_f32_32x32x16_bf16 v[236:251], v[186:189], v[124:127], v[128:143]
	v_add_f32_e32 v160, v73, v160
	v_cvt_pk_bf16_f32 v68, v72, v73
	v_add_f32_e32 v159, v74, v159
	v_add_f32_e32 v160, v75, v160
	v_cvt_pk_bf16_f32 v69, v74, v75
	s_waitcnt lgkmcnt(5)
	v_mfma_f32_32x32x16_bf16 v[96:111], v[190:193], v[120:123], v[96:111]
	v_add_f32_e32 v159, v76, v159
	v_add_f32_e32 v160, v77, v160
	v_cvt_pk_bf16_f32 v70, v76, v77
	v_add_f32_e32 v159, v78, v159
	v_add_f32_e32 v160, v79, v160
	v_cvt_pk_bf16_f32 v71, v78, v79
	s_waitcnt lgkmcnt(4)
	v_mfma_f32_32x32x16_bf16 v[236:251], v[194:197], v[120:123], v[236:251]
	s_lshl_b32 s59, s2, 14
	v_add_u32_e32 v172, s59, v177
	ds_read_b64_tr_b16 v[182:183], v172 offset:0x0
	ds_read_b64_tr_b16 v[184:185], v172 offset:0x800
	ds_read_b64_tr_b16 v[186:187], v172 offset:0x1000
	ds_read_b64_tr_b16 v[188:189], v172 offset:0x1800
	ds_read_b64_tr_b16 v[190:191], v172 offset:0x2000
	ds_read_b64_tr_b16 v[192:193], v172 offset:0x2800
	ds_read_b64_tr_b16 v[194:195], v172 offset:0x3000
	ds_read_b64_tr_b16 v[196:197], v172 offset:0x3800
	v_add_f32_e32 v159, v80, v159
	v_add_f32_e32 v160, v81, v160
	v_cvt_pk_bf16_f32 v72, v80, v81
	v_add_f32_e32 v159, v82, v159
	v_add_f32_e32 v160, v83, v160
	v_cvt_pk_bf16_f32 v73, v82, v83
	s_waitcnt lgkmcnt(11)
	v_mfma_f32_32x32x16_bf16 v[96:111], v[198:201], v[116:119], v[96:111]
	v_add_f32_e32 v159, v84, v159
	v_add_f32_e32 v160, v85, v160
	v_cvt_pk_bf16_f32 v74, v84, v85
	v_add_f32_e32 v159, v86, v159
	v_add_f32_e32 v160, v87, v160
	v_cvt_pk_bf16_f32 v75, v86, v87
	s_waitcnt lgkmcnt(10)
	v_mfma_f32_32x32x16_bf16 v[236:251], v[202:205], v[116:119], v[236:251]
	s_waitcnt lgkmcnt(8)
	ds_read_b64_tr_b16 v[198:199], v172 offset:0x200
	ds_read_b64_tr_b16 v[200:201], v172 offset:0xa00
	ds_read_b64_tr_b16 v[202:203], v172 offset:0x1200
	ds_read_b64_tr_b16 v[204:205], v172 offset:0x1a00
	v_add_f32_e32 v159, v88, v159
	v_add_f32_e32 v160, v89, v160
	v_cvt_pk_bf16_f32 v76, v88, v89
	v_add_f32_e32 v159, v90, v159
	v_add_f32_e32 v160, v91, v160
	v_cvt_pk_bf16_f32 v77, v90, v91
	v_add_f32_e32 v159, v92, v159
	v_mfma_f32_32x32x16_bf16 v[96:111], v[206:209], v[112:115], v[96:111]
	ds_read_b64_tr_b16 v[206:207], v172 offset:0x2200
	ds_read_b64_tr_b16 v[208:209], v172 offset:0x2a00
	v_add_f32_e32 v160, v93, v160
	v_cvt_pk_bf16_f32 v78, v92, v93
	v_add_f32_e32 v159, v94, v159
	v_add_f32_e32 v160, v95, v160
	v_cvt_pk_bf16_f32 v79, v94, v95
	v_add_f32_e32 v159, v159, v160
	v_fma_f32 v167, v167, v235, v159
	v_mfma_f32_32x32x16_bf16 v[236:251], v[210:213], v[112:115], v[236:251]
	s_waitcnt lgkmcnt(12)
	v_mfma_f32_32x32x16_bf16 v[0:15], v[64:67], v[182:185], v[0:15]
	ds_read_b64_tr_b16 v[210:211], v172 offset:0x3200
	ds_read_b64_tr_b16 v[212:213], v172 offset:0x3a00
	v_max3_f32 v161, v96, v97, v98
	v_max3_f32 v161, v161, v99, v100
	v_max3_f32 v161, v161, v101, v102
	v_max3_f32 v161, v161, v103, v104
	s_waitcnt lgkmcnt(12)
	v_mfma_f32_32x32x16_bf16 v[0:15], v[68:71], v[186:189], v[0:15]
	ds_read_b64_tr_b16 v[182:183], v172 offset:0x400
	ds_read_b64_tr_b16 v[184:185], v172 offset:0xc00
	v_max3_f32 v161, v161, v105, v106
	v_max3_f32 v161, v161, v107, v108
	v_max3_f32 v161, v161, v109, v110
	v_max_f32_e32 v161, v161, v111
	s_waitcnt lgkmcnt(12)
	v_mfma_f32_32x32x16_bf16 v[0:15], v[72:75], v[190:193], v[0:15]
	ds_read_b64_tr_b16 v[186:187], v172 offset:0x1400
	ds_read_b64_tr_b16 v[188:189], v172 offset:0x1c00
	v_max3_f32 v216, v236, v237, v238
	v_max3_f32 v216, v216, v239, v240
	v_max3_f32 v216, v216, v241, v242
	v_max3_f32 v216, v216, v243, v244
	s_waitcnt lgkmcnt(12)
	v_mfma_f32_32x32x16_bf16 v[0:15], v[76:79], v[194:197], v[0:15]
	ds_read_b64_tr_b16 v[190:191], v172 offset:0x2400
	ds_read_b64_tr_b16 v[192:193], v172 offset:0x2c00
	v_max3_f32 v216, v216, v245, v246
	v_max3_f32 v216, v216, v247, v248
	v_max3_f32 v216, v216, v249, v250
	v_max_f32_e32 v216, v216, v251
	v_max_f32_e32 v161, v161, v216
	v_cmp_ge_f32_e32 vcc, s66, v161
	s_cmp_eq_u64 vcc, exec
	s_cbranch_scc0 .Lat_rare0
	v_mov_b32_e32 v158, 1.0

; __device__ __forceinline__ void finishSM(f32x16& p0, f32x16& p1, float alpha, float& l_reg, bf16x8& pa0, bf16x8& pa1, bf16x8& pa2, bf16x8& pa3) {
; #pragma unroll
;   for (int r = 0; r < 16; ++r) p1[r] = __builtin_amdgcn_exp2f(p1[r]);
;   float ps = 0;
; #pragma unroll
;   for (int r = 0; r < 16; ++r) ps += p0[r];
; #pragma unroll
;   for (int r = 0; r < 16; ++r) ps += p1[r];
;   { auto rr = __builtin_amdgcn_permlane32_swap(__float_as_uint(ps), __float_as_uint(ps), false, false);
;     ps = __uint_as_float(rr[0]) + __uint_as_float(rr[1]); }
;   l_reg = l_reg * alpha + ps;
;     ...
;   PK4(p0, 0, pa0); PK4(p0, 8, pa1); PK4(p1, 0, pa2); PK4(p1, 8, pa3);
;     ...
; }
; __device__ __forceinline__ void qkt(f32x16& p0, f32x16& p1, const char* Ks, const bf16x8* qr, int r32, int hi, float m_ref) {
; #pragma unroll
;   for (int r = 0; r < 16; ++r) { p0[r] = -m_ref; p1[r] = -m_ref; }
; #pragma unroll
;   for (int d0 = 0; d0 < 4; ++d0) { const int cb = (d0 * 16 + hi * 8) * 2;
;     bf16x8 b0 = *reinterpret_cast<const bf16x8*>(Ks + KSWZ(r32, cb));
;     bf16x8 b1 = *reinterpret_cast<const bf16x8*>(Ks + KSWZ(32 + r32, cb));
;     p0 = __builtin_amdgcn_mfma_f32_32x32x16_bf16(b0, qr[d0], p0, 0, 0, 0);
;     p1 = __builtin_amdgcn_mfma_f32_32x32x16_bf16(b1, qr[d0], p1, 0, 0, 0); }
; }
; __device__ __forceinline__ int v_st(int k, int c) { const int kk = (k & ~0xC) | ((k & 4) << 1) | ((k & 8) >> 1); return ((kk >> 3) * 4 + (c >> 5)) * 512 + ((kk & 7) * 32 + (c & 31)) * 2; }
; __device__ __forceinline__ int v_rd_base(int lane) { return ((lane & 3) << 3) | (((lane >> 2) & 3) << 6) | (((lane >> 4) & 1) << 5) | (((lane >> 5) & 1) << 8); }
; template <int OFF> __device__ __forceinline__ s16x4 tr_read(int vb) {
; __device__ __forceinline__ void attn_unit(const bf16_t* __restrict__ Qb, const bf16_t* __restrict__ Kh, const bf16_t* __restrict__ Vh, int seq, char* lds,
;                                           int mode, float* scratch, float lam, float gscale, const float* __restrict__ subg, bf16_t* outp) {
;     ...
;     SBAR(); qkt(pA0, pA1, K_lds + bc * SHM_K, qr, r32, hi, m_reg);
;     finishSM(pB0, pB1, alB, l_reg, pa0, pa1, pa2, pa3); SBAR();
;     if (j + 3 < NT) SLOAD(SE, (j + 3) * KVBLK); SBAR();
;     pv_d0(o, vb0 + bp * SHM_V, pa0, pa1, pa2, pa3); partialSM(pA0, pA1, m_reg, alA, false);
;     SWAIT(); SWRITE(bn, SO);
;     RESC(alA); __syncthreads(); ROT3();
.Lat_rescback0:
	s_waitcnt vmcnt(3)
	s_barrier
	s_mov_b32 s21, 0
	s_lshl_b32 s20, s2, 14
	s_add_i32 s20, s20, s79
	s_add_i32 m0, s20, s79
	s_nop 0
	global_load_lds_dwordx4 v233, s[24:25]
	s_add_i32 m0, m0, 0x400
	s_nop 0
	global_load_lds_dwordx4 v234, s[24:25]
	s_add_i32 s20, s52, 4
	s_and_b32 s20, s20, 3
	s_lshl_b32 s20, s20, 13
	s_add_i32 s20, s20, s79
	s_add_i32 m0, s20, 0xc000
	s_nop 0
	global_load_lds_dwordx4 v232, s[24:25]
	s_add_u32 s24, s24, 0x10000
	s_addc_u32 s25, s25, 0
	v_add_f32_e32 v159, v96, v97
	v_cvt_pk_bf16_f32 v96, v96, v97
	v_add_f32_e32 v160, v98, v99
	v_cvt_pk_bf16_f32 v97, v98, v99
	v_add_f32_e32 v159, v100, v159
	s_waitcnt lgkmcnt(7)
	v_mfma_f32_32x32x16_bf16 v[64:79], v[182:185], v[124:127], v[128:143]
	v_add_f32_e32 v160, v101, v160
	v_cvt_pk_bf16_f32 v98, v100, v101
	v_add_f32_e32 v159, v102, v159
	v_add_f32_e32 v160, v103, v160
	v_cvt_pk_bf16_f32 v99, v102, v103
	v_add_f32_e32 v159, v104, v159
	s_waitcnt lgkmcnt(6)
	v_mfma_f32_32x32x16_bf16 v[80:95], v[186:189], v[124:127], v[128:143]
	v_add_f32_e32 v160, v105, v160
	v_cvt_pk_bf16_f32 v100, v104, v105
	v_add_f32_e32 v159, v106, v159
	v_add_f32_e32 v160, v107, v160
	v_cvt_pk_bf16_f32 v101, v106, v107
	s_waitcnt lgkmcnt(5)
	v_mfma_f32_32x32x16_bf16 v[64:79], v[190:193], v[120:123], v[64:79]
	v_add_f32_e32 v159, v108, v159
	v_add_f32_e32 v160, v109, v160
	v_cvt_pk_bf16_f32 v102, v108, v109
	v_add_f32_e32 v159, v110, v159
	v_add_f32_e32 v160, v111, v160
	v_cvt_pk_bf16_f32 v103, v110, v111
	s_waitcnt lgkmcnt(4)
	v_mfma_f32_32x32x16_bf16 v[80:95], v[194:197], v[120:123], v[80:95]
	s_lshl_b32 s59, s1, 14
	v_add_u32_e32 v172, s59, v177
	ds_read_b64_tr_b16 v[182:183], v172 offset:0x0
	ds_read_b64_tr_b16 v[184:185], v172 offset:0x800
	ds_read_b64_tr_b16 v[186:187], v172 offset:0x1000
	ds_read_b64_tr_b16 v[188:189], v172 offset:0x1800
	ds_read_b64_tr_b16 v[190:191], v172 offset:0x2000
	ds_read_b64_tr_b16 v[192:193], v172 offset:0x2800
	ds_read_b64_tr_b16 v[194:195], v172 offset:0x3000
	ds_read_b64_tr_b16 v[196:197], v172 offset:0x3800
	v_add_f32_e32 v159, v236, v159
	v_add_f32_e32 v160, v237, v160
	v_cvt_pk_bf16_f32 v104, v236, v237
	v_add_f32_e32 v159, v238, v159
	v_add_f32_e32 v160, v239, v160
	v_cvt_pk_bf16_f32 v105, v238, v239
	s_waitcnt lgkmcnt(11)
	v_mfma_f32_32x32x16_bf16 v[64:79], v[198:201], v[116:119], v[64:79]
	v_add_f32_e32 v159, v240, v159
	v_add_f32_e32 v160, v241, v160
	v_cvt_pk_bf16_f32 v106, v240, v241
	v_add_f32_e32 v159, v242, v159
	v_add_f32_e32 v160, v243, v160
	v_cvt_pk_bf16_f32 v107, v242, v243
	s_waitcnt lgkmcnt(10)
	v_mfma_f32_32x32x16_bf16 v[80:95], v[202:205], v[116:119], v[80:95]
	s_waitcnt lgkmcnt(8)
	ds_read_b64_tr_b16 v[198:199], v172 offset:0x200
	ds_read_b64_tr_b16 v[200:201], v172 offset:0xa00
	ds_read_b64_tr_b16 v[202:203], v172 offset:0x1200
	ds_read_b64_tr_b16 v[204:205], v172 offset:0x1a00
	v_add_f32_e32 v159, v244, v159
	v_add_f32_e32 v160, v245, v160
	v_cvt_pk_bf16_f32 v108, v244, v245
	v_add_f32_e32 v159, v246, v159
	v_add_f32_e32 v160, v247, v160
	v_cvt_pk_bf16_f32 v109, v246, v247
	v_add_f32_e32 v159, v248, v159
	v_mfma_f32_32x32x16_bf16 v[64:79], v[206:209], v[112:115], v[64:79]
	ds_read_b64_tr_b16 v[206:207], v172 offset:0x2200
	ds_read_b64_tr_b16 v[208:209], v172 offset:0x2a00
	v_add_f32_e32 v160, v249, v160
	v_cvt_pk_bf16_f32 v110, v248, v249
	v_add_f32_e32 v159, v250, v159
	v_add_f32_e32 v160, v251, v160
	v_cvt_pk_bf16_f32 v111, v250, v251
	v_add_f32_e32 v159, v159, v160
	v_fma_f32 v167, v167, v158, v159
	v_mfma_f32_32x32x16_bf16 v[80:95], v[210:213], v[112:115], v[80:95]
	s_waitcnt lgkmcnt(12)
	v_mfma_f32_32x32x16_bf16 v[0:15], v[96:99], v[182:185], v[0:15]
	ds_read_b64_tr_b16 v[210:211], v172 offset:0x3200
	ds_read_b64_tr_b16 v[212:213], v172 offset:0x3a00
	v_max3_f32 v161, v64, v65, v66
	v_max3_f32 v161, v161, v67, v68
	v_max3_f32 v161, v161, v69, v70
	v_max3_f32 v161, v161, v71, v72
	s_waitcnt lgkmcnt(12)
	v_mfma_f32_32x32x16_bf16 v[0:15], v[100:103], v[186:189], v[0:15]
	ds_read_b64_tr_b16 v[182:183], v172 offset:0x400
	ds_read_b64_tr_b16 v[184:185], v172 offset:0xc00
	v_max3_f32 v161, v161, v73, v74
	v_max3_f32 v161, v161, v75, v76
	v_max3_f32 v161, v161, v77, v78
	v_max_f32_e32 v161, v161, v79
	s_waitcnt lgkmcnt(12)
	v_mfma_f32_32x32x16_bf16 v[0:15], v[104:107], v[190:193], v[0:15]
	ds_read_b64_tr_b16 v[186:187], v172 offset:0x1400
	ds_read_b64_tr_b16 v[188:189], v172 offset:0x1c00
	v_max3_f32 v216, v80, v81, v82
	v_max3_f32 v216, v216, v83, v84
	v_max3_f32 v216, v216, v85, v86
	v_max3_f32 v216, v216, v87, v88
	s_waitcnt lgkmcnt(12)
	v_mfma_f32_32x32x16_bf16 v[0:15], v[108:111], v[194:197], v[0:15]
	ds_read_b64_tr_b16 v[190:191], v172 offset:0x2400
	ds_read_b64_tr_b16 v[192:193], v172 offset:0x2c00
	v_max3_f32 v216, v216, v89, v90
	v_max3_f32 v216, v216, v91, v92
	v_max3_f32 v216, v216, v93, v94
	v_max_f32_e32 v216, v216, v95
	v_max_f32_e32 v161, v161, v216
	v_cmp_ge_f32_e32 vcc, s66, v161
	s_cmp_eq_u64 vcc, exec
	s_cbranch_scc0 .Lat_rare1
	v_mov_b32_e32 v235, 1.0
